# prep phase: the 15 short-conv Z-row loads of a token issued at the top of the token iteration with the first q loads (one dependent round trip less per token)
# baseline (speedup 1.0000x reference)
.LBB0_409:
	v_lshrrev_b32_e32 v2, 4, v51
	v_and_b32_e32 v2, 0x1fffff8, v2
	v_or_b32_e32 v2, s25, v2
	v_and_b32_e32 v3, 0x7f, v51
	v_lshl_or_b32 v2, v2, 7, v3
	v_cndmask_b32_e64 v128, v51, v2, s[28:29]
	s_movk_i32 s0, 0xfff
	v_cmp_lt_i32_e64 s[0:1], s0, v128
	v_and_b32_e32 v2, 0x3ff, v128
	v_and_b32_e32 v13, 0xff, v128
	v_cndmask_b32_e64 v9, v13, v2, s[0:1]
	v_mov_b64_e32 v[2:3], s[8:9]
	v_mad_i64_i32 v[132:133], s[36:37], v128, s15, v[2:3]
	v_mov_b32_e32 v115, v131
	v_lshl_add_u64 v[2:3], v[132:133], 0, v[114:115]
	v_mov_b32_e32 v117, v131
	v_lshl_add_u64 v[4:5], v[2:3], 0, v[116:117]
	v_mov_b32_e32 v250, 0x102
	v_mov_b32_e32 v251, 0x402
	v_cndmask_b32_e64 v250, v250, v251, s[0:1]
	v_lshlrev_b32_e32 v70, 2, v52
	v_add_u32_e32 v248, 0x1880, v70
	v_mov_b32_e32 v249, 0
	v_lshl_add_u64 v[248:249], s[8:9], 0, v[248:249]
	v_add_u32_e32 v71, -2, v128
	v_cmp_lt_u32_e32 vcc, v9, v250
	v_cmp_lt_u32_e64 s[100:101], 1, v9
	s_and_b64 vcc, vcc, s[100:101]
	s_cbranch_vccz .Lprep_cz0
	v_mad_i64_i32 v[246:247], s[100:101], v71, s15, v[248:249]
	global_load_dwordx4 v[156:159], v[246:247], off
	global_load_dwordx4 v[176:179], v[246:247], off offset:1024
	global_load_dwordx4 v[206:209], v[246:247], off offset:2048
	s_branch .Lprep_cd0

.Lprep_cd0:
	v_add_u32_e32 v71, -1, v128
	v_add_u32_e32 v72, 1, v9
	v_cmp_lt_u32_e32 vcc, v72, v250
	v_cmp_ne_u32_e64 s[100:101], 0, v9
	s_and_b64 vcc, vcc, s[100:101]
	s_cbranch_vccz .Lprep_cz1
	v_mad_i64_i32 v[246:247], s[100:101], v71, s15, v[248:249]
	global_load_dwordx4 v[160:163], v[246:247], off
	global_load_dwordx4 v[180:183], v[246:247], off offset:1024
	global_load_dwordx4 v[210:213], v[246:247], off offset:2048
	s_branch .Lprep_cd1

.Lprep_cd1:
	v_add_u32_e32 v72, 2, v9
	v_cmp_lt_u32_e32 vcc, v72, v250
	s_cbranch_vccz .Lprep_cz2
	v_mad_i64_i32 v[246:247], s[100:101], v128, s15, v[248:249]
	global_load_dwordx4 v[164:167], v[246:247], off
	global_load_dwordx4 v[184:187], v[246:247], off offset:1024
	global_load_dwordx4 v[214:217], v[246:247], off offset:2048
	s_branch .Lprep_cd2

.Lprep_cd2:
	v_add_u32_e32 v71, 1, v128
	v_add_u32_e32 v72, 3, v9
	v_cmp_lt_u32_e32 vcc, v72, v250
	s_cbranch_vccz .Lprep_cz3
	v_mad_i64_i32 v[246:247], s[100:101], v71, s15, v[248:249]
	global_load_dwordx4 v[168:171], v[246:247], off
	global_load_dwordx4 v[188:191], v[246:247], off offset:1024
	global_load_dwordx4 v[218:221], v[246:247], off offset:2048
	s_branch .Lprep_cd3

.Lprep_cd3:
	v_add_u32_e32 v71, 2, v128
	v_add_u32_e32 v72, 4, v9
	v_cmp_lt_u32_e32 vcc, v72, v250
	s_cbranch_vccz .Lprep_cz4
	v_mad_i64_i32 v[246:247], s[100:101], v71, s15, v[248:249]
	global_load_dwordx4 v[172:175], v[246:247], off
	global_load_dwordx4 v[192:195], v[246:247], off offset:1024
	global_load_dwordx4 v[222:225], v[246:247], off offset:2048
	s_branch .Lprep_cd4

.Lprep_cd4:
	global_load_dwordx2 v[10:11], v[4:5], off offset:128
	global_load_dwordx2 v[2:3], v[4:5], off offset:192
	v_lshrrev_b32_e32 v6, 6, v9
	v_cvt_f32_ubyte0_e32 v12, v6
	v_and_b32_e32 v22, 63, v9
	v_cmp_gt_i32_e32 vcc, s33, v128
	s_waitcnt vmcnt(1)
	v_mov_b32_e32 v14, v11
	s_waitcnt vmcnt(0)
	v_mov_b32_e32 v15, v3
	v_mov_b32_e32 v6, v10
	v_mov_b32_e32 v7, v2
	v_pk_mul_f32 v[14:15], v[14:15], v[14:15]
	s_nop 0
	v_pk_fma_f32 v[6:7], v[6:7], v[6:7], v[14:15]
	global_load_dwordx2 v[14:15], v[4:5], off
	s_nop 0
	global_load_dwordx2 v[4:5], v[4:5], off offset:64
	s_waitcnt vmcnt(1)
	v_mov_b32_e32 v18, v15
	s_waitcnt vmcnt(0)
	v_mov_b32_e32 v19, v5
	v_mov_b32_e32 v16, v14
	v_mov_b32_e32 v17, v4
	v_pk_mul_f32 v[18:19], v[18:19], v[18:19]
	s_nop 0
	v_pk_fma_f32 v[16:17], v[16:17], v[16:17], v[18:19]
	global_load_dwordx2 v[18:19], v[48:49], off
	global_load_dwordx2 v[20:21], v[48:49], off offset:64
	v_add_f32_e32 v8, v16, v17
	v_add_f32_e32 v6, v8, v6
	v_add_f32_e32 v6, v6, v7
	ds_bpermute_b32 v7, v69, v6
	s_waitcnt lgkmcnt(0)
	v_add_f32_e32 v6, v6, v7
	ds_bpermute_b32 v7, v79, v6
	s_waitcnt lgkmcnt(0)
	v_add_f32_e32 v6, v6, v7
	ds_bpermute_b32 v7, v138, v6
	s_waitcnt lgkmcnt(0)
	v_add_f32_e32 v6, v6, v7
	v_fmamk_f32 v6, v6, 0x3c800000, v197
	v_cmp_gt_f32_e64 s[36:37], s14, v6
	v_mul_f32_e32 v7, 0x4b800000, v6
	s_nop 0
	v_cndmask_b32_e64 v6, v6, v7, s[36:37]
	v_rsq_f32_e32 v6, v6
	s_nop 0
	v_mul_f32_e32 v7, 0x45800000, v6
	v_cndmask_b32_e64 v8, v6, v7, s[36:37]
	s_waitcnt vmcnt(1)
	v_pk_mul_f32 v[6:7], v[18:19], v[8:9] op_sel_hi:[1,0]
	s_nop 0
	v_pk_mul_f32 v[6:7], v[14:15], v[6:7]
	s_waitcnt vmcnt(0)
	v_pk_mul_f32 v[14:15], v[20:21], v[8:9] op_sel_hi:[1,0]
	s_nop 0
	v_pk_mul_f32 v[4:5], v[4:5], v[14:15]
	global_load_dwordx2 v[14:15], v[48:49], off offset:128
	s_waitcnt vmcnt(0)
	v_pk_mul_f32 v[14:15], v[14:15], v[8:9] op_sel_hi:[1,0]
	s_nop 0
	v_pk_mul_f32 v[10:11], v[10:11], v[14:15]
	global_load_dwordx2 v[14:15], v[48:49], off offset:192
	s_waitcnt vmcnt(0)
	v_pk_mul_f32 v[14:15], v[14:15], v[8:9] op_sel_hi:[1,0]
	s_nop 0
	v_pk_mul_f32 v[2:3], v[2:3], v[14:15]
	v_cvt_f32_ubyte0_e32 v8, v22
	s_and_saveexec_b64 s[36:37], s[0:1]
	s_cbranch_execz .LBB0_411
	v_mul_f32_e32 v15, v53, v8
	v_mul_f32_e32 v15, 0.15915494, v15
	v_mul_f32_e32 v14, v53, v12
	v_cos_f32_e32 v18, v15
	v_sin_f32_e32 v20, v15
	v_mul_f32_e32 v15, v142, v12
	v_mul_f32_e32 v16, 0.15915494, v14
	v_mul_f32_e32 v19, v142, v8
	v_mul_f32_e32 v17, 0.15915494, v15
	v_cos_f32_e32 v14, v16
	v_sin_f32_e32 v16, v16
	v_cos_f32_e32 v15, v17
	v_sin_f32_e32 v17, v17
	v_mul_f32_e32 v21, 0.15915494, v19
	v_cos_f32_e32 v19, v21
	v_sin_f32_e32 v21, v21
	v_pk_mul_f32 v[22:23], v[16:17], v[4:5]
	v_pk_mul_f32 v[4:5], v[14:15], v[4:5]
	v_pk_fma_f32 v[22:23], v[14:15], v[6:7], v[22:23] neg_lo:[0,0,1] neg_hi:[0,0,1]
	v_pk_fma_f32 v[4:5], v[16:17], v[6:7], v[4:5]
	v_pk_mul_f32 v[6:7], v[20:21], v[2:3]
	v_pk_mul_f32 v[2:3], v[18:19], v[2:3]
	v_pk_fma_f32 v[6:7], v[18:19], v[10:11], v[6:7] neg_lo:[0,0,1] neg_hi:[0,0,1]
	v_pk_fma_f32 v[2:3], v[20:21], v[10:11], v[2:3]
	v_mov_b64_e32 v[10:11], v[6:7]
	v_mov_b64_e32 v[6:7], v[22:23]

.LBB0_417:
	s_or_b64 exec, exec, s[0:1]
	v_lshlrev_b64 v[4:5], 7, v[128:129]
	s_waitcnt vmcnt(0)
	v_cvt_pk_bf16_f32 v6, v2, v3
	v_lshl_add_u64 v[2:3], v[4:5], 1, v[54:55]
	v_cmp_lt_u32_e32 vcc, 1, v9
	v_cmp_lt_u32_e64 s[0:1], v9, v8
	v_mov_b32_e32 v130, v131
	global_store_dword v[2:3], v6, off
	global_load_dwordx4 v[226:229], v[60:61], off
	global_load_dwordx4 v[230:233], v[62:63], off offset:-3072
	global_load_dwordx4 v[234:237], v[62:63], off
	global_load_dwordx4 v[238:241], v[64:65], off
	global_load_dwordx4 v[242:245], v[66:67], off
	s_waitcnt vmcnt(0)
	v_pk_fma_f32 v[6:7], v[156:157], v[226:227], 0 op_sel_hi:[1,1,0]
	v_pk_fma_f32 v[4:5], v[158:159], v[228:229], 0 op_sel_hi:[1,1,0]
	v_pk_fma_f32 v[6:7], v[160:161], v[230:231], v[6:7]
	v_pk_fma_f32 v[4:5], v[162:163], v[232:233], v[4:5]
	v_pk_fma_f32 v[6:7], v[164:165], v[234:235], v[6:7]
	v_pk_fma_f32 v[4:5], v[166:167], v[236:237], v[4:5]
	v_pk_fma_f32 v[6:7], v[168:169], v[238:239], v[6:7]
	v_pk_fma_f32 v[4:5], v[170:171], v[240:241], v[4:5]
	v_pk_fma_f32 v[6:7], v[172:173], v[242:243], v[6:7]
	v_pk_fma_f32 v[4:5], v[174:175], v[244:245], v[4:5]
	global_load_dwordx4 v[226:229], v[60:61], off offset:1024
	global_load_dwordx4 v[230:233], v[62:63], off offset:-2048
	global_load_dwordx4 v[234:237], v[62:63], off offset:1024
	global_load_dwordx4 v[238:241], v[64:65], off offset:1024
	global_load_dwordx4 v[242:245], v[66:67], off offset:1024
	v_mul_f32_e32 v2, 0xbfb8aa3b, v5
	v_exp_f32_e32 v9, v2
	v_mul_f32_e32 v2, 0xbfb8aa3b, v4
	v_exp_f32_e32 v8, v2
	v_mul_f32_e32 v2, 0xbfb8aa3b, v7
	v_exp_f32_e32 v17, v2
	v_mul_f32_e32 v2, 0xbfb8aa3b, v6
	v_exp_f32_e32 v16, v2
	v_pk_add_f32 v[8:9], v[8:9], 1.0 op_sel_hi:[1,0]
	v_mad_i64_i32 v[2:3], s[50:51], v128, s12, v[112:113]
	v_pk_add_f32 v[16:17], v[16:17], 1.0 op_sel_hi:[1,0]
	v_mov_b32_e32 v130, v131
	v_div_scale_f32 v18, s[50:51], v17, v17, v7
	v_rcp_f32_e32 v19, v18
	s_nop 0
	v_fma_f32 v20, -v18, v19, 1.0
	v_fmac_f32_e32 v19, v20, v19
	v_div_scale_f32 v20, vcc, v7, v17, v7
	v_mul_f32_e32 v21, v20, v19
	v_fma_f32 v22, -v18, v21, v20
	v_fmac_f32_e32 v21, v22, v19
	v_fma_f32 v18, -v18, v21, v20
	v_div_fmas_f32 v18, v18, v19, v21
	v_div_fixup_f32 v17, v18, v17, v7
	v_div_scale_f32 v7, s[50:51], v16, v16, v6
	v_rcp_f32_e32 v18, v7
	s_nop 0
	v_fma_f32 v19, -v7, v18, 1.0
	v_fmac_f32_e32 v18, v19, v18
	v_div_scale_f32 v19, vcc, v6, v16, v6
	v_mul_f32_e32 v20, v19, v18
	v_fma_f32 v21, -v7, v20, v19
	v_fmac_f32_e32 v20, v21, v18
	v_fma_f32 v7, -v7, v20, v19
	v_div_fmas_f32 v7, v7, v18, v20
	v_div_scale_f32 v18, s[50:51], v9, v9, v5
	v_rcp_f32_e32 v19, v18
	v_div_fixup_f32 v16, v7, v16, v6
	v_pk_mul_f32 v[6:7], v[16:17], v[16:17]
	v_fma_f32 v20, -v18, v19, 1.0
	v_fmac_f32_e32 v19, v20, v19
	v_div_scale_f32 v20, vcc, v5, v9, v5
	v_mul_f32_e32 v21, v20, v19
	v_fma_f32 v22, -v18, v21, v20
	v_fmac_f32_e32 v21, v22, v19
	v_fma_f32 v18, -v18, v21, v20
	v_div_fmas_f32 v18, v18, v19, v21
	v_div_fixup_f32 v5, v18, v9, v5
	v_div_scale_f32 v9, s[50:51], v8, v8, v4
	v_rcp_f32_e32 v18, v9
	v_add_f32_e32 v6, v6, v7
	v_fma_f32 v19, -v9, v18, 1.0
	v_fmac_f32_e32 v18, v19, v18
	v_div_scale_f32 v19, vcc, v4, v8, v4
	v_mul_f32_e32 v20, v19, v18
	v_fma_f32 v21, -v9, v20, v19
	v_fmac_f32_e32 v20, v21, v18
	v_fma_f32 v9, -v9, v20, v19
	v_div_fmas_f32 v9, v9, v18, v20
	v_div_fixup_f32 v4, v9, v8, v4
	v_pk_mul_f32 v[8:9], v[4:5], v[4:5]
	s_nop 0
	v_add_f32_e32 v6, v6, v8
	v_add_f32_e32 v6, v6, v9
	ds_bpermute_b32 v7, v69, v6
	s_waitcnt lgkmcnt(0)
	v_add_f32_e32 v6, v6, v7
	ds_bpermute_b32 v7, v79, v6
	s_waitcnt lgkmcnt(0)
	v_add_f32_e32 v6, v6, v7
	ds_bpermute_b32 v7, v138, v6
	s_waitcnt lgkmcnt(0)
	v_add_f32_e32 v6, v6, v7
	ds_bpermute_b32 v7, v139, v6
	s_waitcnt lgkmcnt(0)
	v_add_f32_e32 v6, v6, v7
	v_add_f32_e32 v6, 0x358637bd, v6
	v_cmp_gt_f32_e32 vcc, s14, v6
	v_mul_f32_e32 v7, 0x4b800000, v6
	s_nop 0
	v_cndmask_b32_e32 v6, v6, v7, vcc
	v_rsq_f32_e32 v6, v6
	s_nop 0
	v_mul_f32_e32 v7, 0x45800000, v6
	v_cndmask_b32_e32 v6, v6, v7, vcc
	v_mul_f32_e32 v8, 0x3e000000, v6
	v_pk_mul_f32 v[6:7], v[4:5], v[8:9] op_sel_hi:[1,0]
	v_pk_mul_f32 v[4:5], v[16:17], v[8:9] op_sel_hi:[1,0]
	global_store_dwordx4 v[2:3], v[4:7], off
	v_lshlrev_b32_e32 v8, 2, v68
	s_nop 0
	v_mov_b64_e32 v[6:7], v[130:131]
	v_mov_b64_e32 v[4:5], v[130:131]
	s_waitcnt vmcnt(1)
	v_pk_fma_f32 v[6:7], v[176:177], v[226:227], 0 op_sel_hi:[1,1,0]
	v_pk_fma_f32 v[4:5], v[178:179], v[228:229], 0 op_sel_hi:[1,1,0]
	v_pk_fma_f32 v[6:7], v[180:181], v[230:231], v[6:7]
	v_pk_fma_f32 v[4:5], v[182:183], v[232:233], v[4:5]
	v_pk_fma_f32 v[6:7], v[184:185], v[234:235], v[6:7]
	v_pk_fma_f32 v[4:5], v[186:187], v[236:237], v[4:5]
	v_pk_fma_f32 v[6:7], v[188:189], v[238:239], v[6:7]
	v_pk_fma_f32 v[4:5], v[190:191], v[240:241], v[4:5]
	v_pk_fma_f32 v[6:7], v[192:193], v[242:243], v[6:7]
	v_pk_fma_f32 v[4:5], v[194:195], v[244:245], v[4:5]
	global_load_dwordx4 v[226:229], v[60:61], off offset:2048
	global_load_dwordx4 v[230:233], v[62:63], off offset:-1024
	global_load_dwordx4 v[234:237], v[62:63], off offset:2048
	global_load_dwordx4 v[238:241], v[64:65], off offset:2048
	global_load_dwordx4 v[242:245], v[66:67], off offset:2048
	v_mul_f32_e32 v16, 0xbfb8aa3b, v7
	v_exp_f32_e32 v17, v16
	v_mul_f32_e32 v16, 0xbfb8aa3b, v6
	v_exp_f32_e32 v16, v16
	v_mul_f32_e32 v8, 0xbfb8aa3b, v5
	v_exp_f32_e32 v9, v8
	v_mul_f32_e32 v8, 0xbfb8aa3b, v4
	v_pk_add_f32 v[16:17], v[16:17], 1.0 op_sel_hi:[1,0]
	v_exp_f32_e32 v8, v8
	v_div_scale_f32 v18, s[50:51], v17, v17, v7
	v_rcp_f32_e32 v19, v18
	v_pk_add_f32 v[8:9], v[8:9], 1.0 op_sel_hi:[1,0]
	v_mov_b32_e32 v130, v131
	v_fma_f32 v20, -v18, v19, 1.0
	v_fmac_f32_e32 v19, v20, v19
	v_div_scale_f32 v20, vcc, v7, v17, v7
	v_mul_f32_e32 v21, v20, v19
	v_fma_f32 v22, -v18, v21, v20
	v_fmac_f32_e32 v21, v22, v19
	v_fma_f32 v18, -v18, v21, v20
	v_div_fmas_f32 v18, v18, v19, v21
	v_div_fixup_f32 v17, v18, v17, v7
	v_div_scale_f32 v7, s[50:51], v16, v16, v6
	v_rcp_f32_e32 v18, v7
	s_nop 0
	v_fma_f32 v19, -v7, v18, 1.0
	v_fmac_f32_e32 v18, v19, v18
	v_div_scale_f32 v19, vcc, v6, v16, v6
	v_mul_f32_e32 v20, v19, v18
	v_fma_f32 v21, -v7, v20, v19
	v_fmac_f32_e32 v20, v21, v18
	v_fma_f32 v7, -v7, v20, v19
	v_div_fmas_f32 v7, v7, v18, v20
	v_div_scale_f32 v18, s[50:51], v9, v9, v5
	v_rcp_f32_e32 v19, v18
	v_div_fixup_f32 v16, v7, v16, v6
	v_pk_mul_f32 v[6:7], v[16:17], v[16:17]
	v_fma_f32 v20, -v18, v19, 1.0
	v_fmac_f32_e32 v19, v20, v19
	v_div_scale_f32 v20, vcc, v5, v9, v5
	v_mul_f32_e32 v21, v20, v19
	v_fma_f32 v22, -v18, v21, v20
	v_fmac_f32_e32 v21, v22, v19
	v_fma_f32 v18, -v18, v21, v20
	v_div_fmas_f32 v18, v18, v19, v21
	v_div_fixup_f32 v5, v18, v9, v5
	v_div_scale_f32 v9, s[50:51], v8, v8, v4
	v_rcp_f32_e32 v18, v9
	v_add_f32_e32 v6, v6, v7
	v_fma_f32 v19, -v9, v18, 1.0
	v_fmac_f32_e32 v18, v19, v18
	v_div_scale_f32 v19, vcc, v4, v8, v4
	v_mul_f32_e32 v20, v19, v18
	v_fma_f32 v21, -v9, v20, v19
	v_fmac_f32_e32 v20, v21, v18
	v_fma_f32 v9, -v9, v20, v19
	v_div_fmas_f32 v9, v9, v18, v20
	v_div_fixup_f32 v4, v9, v8, v4
	v_pk_mul_f32 v[8:9], v[4:5], v[4:5]
	s_nop 0
	v_add_f32_e32 v6, v6, v8
	v_add_f32_e32 v6, v6, v9
	ds_bpermute_b32 v7, v69, v6
	s_waitcnt lgkmcnt(0)
	v_add_f32_e32 v6, v6, v7
	ds_bpermute_b32 v7, v79, v6
	s_waitcnt lgkmcnt(0)
	v_add_f32_e32 v6, v6, v7
	ds_bpermute_b32 v7, v138, v6
	s_waitcnt lgkmcnt(0)
	v_add_f32_e32 v6, v6, v7
	ds_bpermute_b32 v7, v139, v6
	s_waitcnt lgkmcnt(0)
	v_add_f32_e32 v6, v6, v7
	v_add_f32_e32 v6, 0x358637bd, v6
	v_cmp_gt_f32_e32 vcc, s14, v6
	v_mul_f32_e32 v7, 0x4b800000, v6
	s_nop 0
	v_cndmask_b32_e32 v6, v6, v7, vcc
	v_rsq_f32_e32 v6, v6
	s_nop 0
	v_mul_f32_e32 v7, 0x45800000, v6
	v_cndmask_b32_e32 v8, v6, v7, vcc
	v_pk_mul_f32 v[6:7], v[4:5], v[8:9] op_sel_hi:[1,0]
	v_pk_mul_f32 v[4:5], v[16:17], v[8:9] op_sel_hi:[1,0]
	global_store_dwordx4 v[2:3], v[4:7], off offset:1024
	v_lshlrev_b32_e32 v8, 2, v78
	s_nop 0
	v_mov_b64_e32 v[6:7], v[130:131]
	v_mov_b64_e32 v[4:5], v[130:131]
	s_waitcnt vmcnt(1)
	v_pk_fma_f32 v[6:7], v[206:207], v[226:227], 0 op_sel_hi:[1,1,0]
	v_pk_fma_f32 v[4:5], v[208:209], v[228:229], 0 op_sel_hi:[1,1,0]
	v_pk_fma_f32 v[6:7], v[210:211], v[230:231], v[6:7]
	v_pk_fma_f32 v[4:5], v[212:213], v[232:233], v[4:5]
	v_pk_fma_f32 v[6:7], v[214:215], v[234:235], v[6:7]
	v_pk_fma_f32 v[4:5], v[216:217], v[236:237], v[4:5]
	v_pk_fma_f32 v[6:7], v[218:219], v[238:239], v[6:7]
	v_pk_fma_f32 v[4:5], v[220:221], v[240:241], v[4:5]
	v_pk_fma_f32 v[6:7], v[222:223], v[242:243], v[6:7]
	v_pk_fma_f32 v[4:5], v[224:225], v[244:245], v[4:5]
	v_mul_f32_e32 v10, 0xbfb8aa3b, v7
	v_exp_f32_e32 v11, v10
	v_mul_f32_e32 v10, 0xbfb8aa3b, v6
	v_exp_f32_e32 v10, v10
	v_mul_f32_e32 v8, 0xbfb8aa3b, v5
	v_exp_f32_e32 v9, v8
	v_mul_f32_e32 v8, 0xbfb8aa3b, v4
	v_pk_add_f32 v[10:11], v[10:11], 1.0 op_sel_hi:[1,0]
	v_exp_f32_e32 v8, v8
	v_div_scale_f32 v12, s[0:1], v11, v11, v7
	v_rcp_f32_e32 v13, v12
	v_pk_add_f32 v[8:9], v[8:9], 1.0 op_sel_hi:[1,0]
	v_mov_b32_e32 v127, v131
	s_mov_b32 s20, 0x800000
	v_fma_f32 v16, -v12, v13, 1.0
	v_fmac_f32_e32 v13, v16, v13
	v_div_scale_f32 v16, vcc, v7, v11, v7
	v_mul_f32_e32 v17, v16, v13
	v_fma_f32 v18, -v12, v17, v16
	v_fmac_f32_e32 v17, v18, v13
	v_fma_f32 v12, -v12, v17, v16
	v_div_fmas_f32 v12, v12, v13, v17
	v_div_fixup_f32 v7, v12, v11, v7
	v_div_scale_f32 v11, s[0:1], v10, v10, v6
	v_rcp_f32_e32 v12, v11
	s_mov_b32 s27, 0x3f317217
	s_mov_b32 s40, 0x7f800000
	s_mov_b32 s41, 0xc1a00000
	v_fma_f32 v13, -v11, v12, 1.0
	v_fmac_f32_e32 v12, v13, v12
	v_div_scale_f32 v13, vcc, v6, v10, v6
	v_mul_f32_e32 v16, v13, v12
	v_fma_f32 v17, -v11, v16, v13
	v_fmac_f32_e32 v16, v17, v12
	v_fma_f32 v11, -v11, v16, v13
	v_div_fmas_f32 v11, v11, v12, v16
	v_div_fixup_f32 v6, v11, v10, v6
	v_div_scale_f32 v10, s[0:1], v9, v9, v5
	v_rcp_f32_e32 v11, v10
	s_mov_b32 s50, 0xbd800000
	s_mov_b32 s14, 0x800000
	s_mov_b32 s48, 0x3f317217
	v_fma_f32 v12, -v10, v11, 1.0
	v_fmac_f32_e32 v11, v12, v11
	v_div_scale_f32 v12, vcc, v5, v9, v5
	v_mul_f32_e32 v13, v12, v11
	v_fma_f32 v16, -v10, v13, v12
	v_fmac_f32_e32 v13, v16, v11
	v_fma_f32 v10, -v10, v13, v12
	v_div_fmas_f32 v10, v10, v11, v13
	v_div_fixup_f32 v9, v10, v9, v5
	v_div_scale_f32 v5, s[0:1], v8, v8, v4
	v_rcp_f32_e32 v10, v5
	s_nop 0
	v_fma_f32 v11, -v5, v10, 1.0
	v_fmac_f32_e32 v10, v11, v10
	v_div_scale_f32 v11, vcc, v4, v8, v4
	v_mul_f32_e32 v12, v11, v10
	v_fma_f32 v13, -v5, v12, v11
	v_fmac_f32_e32 v12, v13, v10
	v_fma_f32 v5, -v5, v12, v11
	v_div_fmas_f32 v5, v5, v10, v12
	v_div_fixup_f32 v8, v5, v8, v4
	global_store_dwordx4 v[2:3], v[6:9], off offset:2048
	v_lshl_add_u64 v[2:3], v[132:133], 0, v[126:127]
	v_lshl_add_u64 v[16:17], v[2:3], 0, s[54:55]
	v_add_co_u32_e32 v2, vcc, s33, v2
	s_nop 1
	v_addc_co_u32_e32 v3, vcc, 0, v3, vcc
	global_load_dwordx4 v[10:13], v[2:3], off offset:2048
	s_nop 0
	global_load_dwordx4 v[2:5], v[16:17], off offset:48
	global_load_dwordx4 v[6:9], v[16:17], off offset:32
	s_nop 0
	global_load_dwordx4 v[16:19], v[16:17], off offset:16
	s_nop 0
	global_load_dwordx4 v[20:23], v[56:57], off
	global_load_dwordx4 v[24:27], v[88:89], off
	global_load_dwordx4 v[28:31], v[88:89], off offset:512
	global_load_dwordx4 v[32:35], v[88:89], off offset:1024
	global_load_dwordx4 v[36:39], v[88:89], off offset:1536
	global_load_dwordx4 v[134:137], v[88:89], off offset:2048
	global_load_dwordx4 v[144:147], v[88:89], off offset:2560
	global_load_dwordx4 v[148:151], v[88:89], off offset:3072
	global_load_dwordx4 v[152:155], v[88:89], off offset:3584
	s_waitcnt vmcnt(7)
	v_pk_fma_f32 v[20:21], v[10:11], v[24:25], v[20:21] op_sel_hi:[0,1,1]
	v_pk_fma_f32 v[22:23], v[10:11], v[26:27], v[22:23] op_sel_hi:[0,1,1]
	s_waitcnt vmcnt(6)
	v_pk_fma_f32 v[20:21], v[10:11], v[28:29], v[20:21] op_sel:[1,0,0]
	v_pk_fma_f32 v[10:11], v[10:11], v[30:31], v[22:23] op_sel:[1,0,0]
	v_mov_b32_e32 v24, v13
	s_waitcnt vmcnt(5)
	v_pk_fma_f32 v[10:11], v[12:13], v[34:35], v[10:11] op_sel_hi:[0,1,1]
	s_waitcnt vmcnt(4)
	v_pk_fma_f32 v[10:11], v[24:25], v[38:39], v[10:11] op_sel_hi:[0,1,1]
	v_pk_fma_f32 v[20:21], v[12:13], v[32:33], v[20:21] op_sel_hi:[0,1,1]
	s_waitcnt vmcnt(3)
	v_pk_fma_f32 v[10:11], v[16:17], v[136:137], v[10:11] op_sel_hi:[0,1,1]
	v_pk_fma_f32 v[20:21], v[24:25], v[36:37], v[20:21] op_sel_hi:[0,1,1]
	s_waitcnt vmcnt(2)
	v_pk_fma_f32 v[10:11], v[16:17], v[146:147], v[10:11] op_sel:[1,0,0]
	v_pk_fma_f32 v[20:21], v[16:17], v[134:135], v[20:21] op_sel_hi:[0,1,1]
	v_mov_b32_e32 v28, v19
	s_waitcnt vmcnt(1)
	v_pk_fma_f32 v[10:11], v[18:19], v[150:151], v[10:11] op_sel_hi:[0,1,1]
	v_pk_fma_f32 v[20:21], v[16:17], v[144:145], v[20:21] op_sel:[1,0,0]
	v_lshl_add_u64 v[134:135], v[58:59], 0, v[14:15]
	global_load_dwordx4 v[14:17], v[92:93], off
	s_waitcnt vmcnt(1)
	v_pk_fma_f32 v[136:137], v[28:29], v[154:155], v[10:11] op_sel_hi:[0,1,1]
	global_load_dwordx4 v[10:13], v[90:91], off
	global_load_dwordx4 v[22:25], v[96:97], off
	v_pk_fma_f32 v[20:21], v[18:19], v[148:149], v[20:21] op_sel_hi:[0,1,1]
	v_pk_fma_f32 v[20:21], v[28:29], v[152:153], v[20:21] op_sel_hi:[0,1,1]
	global_load_dwordx4 v[30:33], v[100:101], off
	global_load_dwordx4 v[34:37], v[102:103], off
	global_load_dwordx4 v[38:41], v[104:105], off
	global_load_dwordx4 v[26:29], v[98:99], off
	s_waitcnt vmcnt(5)
	v_pk_fma_f32 v[10:11], v[6:7], v[10:11], v[20:21] op_sel_hi:[0,1,1]
	global_load_dwordx4 v[18:21], v[94:95], off
	v_pk_fma_f32 v[10:11], v[6:7], v[14:15], v[10:11] op_sel:[1,0,0]
	v_pk_fma_f32 v[12:13], v[6:7], v[12:13], v[136:137] op_sel_hi:[0,1,1]
	v_pk_fma_f32 v[6:7], v[6:7], v[16:17], v[12:13] op_sel:[1,0,0]
	s_waitcnt vmcnt(0)
	v_pk_fma_f32 v[14:15], v[8:9], v[18:19], v[10:11] op_sel_hi:[0,1,1]
	v_mov_b32_e32 v10, v9
	v_pk_fma_f32 v[14:15], v[10:11], v[22:23], v[14:15] op_sel_hi:[0,1,1]
	v_pk_fma_f32 v[14:15], v[2:3], v[26:27], v[14:15] op_sel_hi:[0,1,1]
	v_pk_fma_f32 v[14:15], v[2:3], v[30:31], v[14:15] op_sel:[1,0,0]
	v_mov_b32_e32 v18, v5
	v_pk_fma_f32 v[14:15], v[4:5], v[34:35], v[14:15] op_sel_hi:[0,1,1]
	v_pk_fma_f32 v[14:15], v[18:19], v[38:39], v[14:15] op_sel_hi:[0,1,1]
	v_mul_f32_e32 v5, 0xbfb8aa3b, v14
	v_exp_f32_e32 v5, v5
	s_nop 0
	v_add_f32_e32 v5, 1.0, v5
	v_cmp_gt_f32_e32 vcc, s20, v5
	s_nop 1
	v_cndmask_b32_e64 v9, 0, 32, vcc
	v_ldexp_f32 v5, v5, v9
	v_log_f32_e32 v5, v5
	s_nop 0
	v_mul_f32_e32 v9, 0x3f317217, v5
	v_fma_f32 v9, v5, s27, -v9
	v_fmac_f32_e32 v9, 0x3377d1cf, v5
	v_fmac_f32_e32 v9, 0x3f317217, v5
	v_cmp_lt_f32_e64 s[0:1], |v5|, s40
	s_nop 1
	v_cndmask_b32_e64 v5, v5, v9, s[0:1]
	v_cndmask_b32_e32 v9, 0, v203, vcc
	v_sub_f32_e32 v5, v5, v9
	v_mul_f32_e32 v9, 0xbfb8aa3b, v15
	v_exp_f32_e32 v9, v9
	v_cmp_gt_f32_e32 vcc, s41, v14
	v_cmp_gt_f32_e64 s[0:1], s41, v15
	v_add_f32_e32 v9, 1.0, v9
	v_cmp_gt_f32_e64 s[36:37], s20, v9
	v_cndmask_b32_e64 v14, v5, -v14, vcc
	s_nop 0
	v_cndmask_b32_e64 v11, 0, 32, s[36:37]
	v_ldexp_f32 v9, v9, v11
	v_log_f32_e32 v9, v9
	s_nop 0
	v_mul_f32_e32 v11, 0x3f317217, v9
	v_fma_f32 v11, v9, s27, -v11
	v_fmac_f32_e32 v11, 0x3377d1cf, v9
	v_fmac_f32_e32 v11, 0x3f317217, v9
	v_cmp_lt_f32_e64 s[38:39], |v9|, s40
	s_nop 1
	v_cndmask_b32_e64 v9, v9, v11, s[38:39]
	v_cndmask_b32_e64 v11, 0, v203, s[36:37]
	v_sub_f32_e32 v9, v9, v11
	v_pk_fma_f32 v[6:7], v[8:9], v[20:21], v[6:7] op_sel_hi:[0,1,1]
	v_pk_fma_f32 v[6:7], v[10:11], v[24:25], v[6:7] op_sel_hi:[0,1,1]
	v_pk_fma_f32 v[6:7], v[2:3], v[28:29], v[6:7] op_sel_hi:[0,1,1]
	v_pk_fma_f32 v[2:3], v[2:3], v[32:33], v[6:7] op_sel:[1,0,0]
	v_cndmask_b32_e64 v15, v9, -v15, s[0:1]
	v_pk_fma_f32 v[2:3], v[4:5], v[36:37], v[2:3] op_sel_hi:[0,1,1]
	v_pk_fma_f32 v[2:3], v[18:19], v[40:41], v[2:3] op_sel_hi:[0,1,1]
	v_mul_f32_e32 v4, 0xbfb8aa3b, v2
	v_exp_f32_e32 v4, v4
	v_pk_mul_f32 v[14:15], v[14:15], s[50:51] op_sel_hi:[1,0]
	v_add_f32_e32 v4, 1.0, v4
	v_cmp_gt_f32_e32 vcc, s20, v4
	s_nop 1
	v_cndmask_b32_e64 v5, 0, 32, vcc
	v_ldexp_f32 v4, v4, v5
	v_log_f32_e32 v4, v4
	s_nop 0
	v_mul_f32_e32 v5, 0x3f317217, v4
	v_fma_f32 v5, v4, s27, -v5
	v_fmac_f32_e32 v5, 0x3377d1cf, v4
	v_fmac_f32_e32 v5, 0x3f317217, v4
	v_cmp_lt_f32_e64 s[0:1], |v4|, s40
	s_nop 1
	v_cndmask_b32_e64 v4, v4, v5, s[0:1]
	v_cndmask_b32_e32 v5, 0, v203, vcc
	v_sub_f32_e32 v4, v4, v5
	v_mul_f32_e32 v5, 0xbfb8aa3b, v3
	v_exp_f32_e32 v5, v5
	v_cmp_gt_f32_e32 vcc, s41, v2
	v_cmp_gt_f32_e64 s[0:1], s41, v3
	v_add_f32_e32 v5, 1.0, v5
	v_cmp_gt_f32_e64 s[36:37], s20, v5
	v_cndmask_b32_e64 v2, v4, -v2, vcc
	s_nop 0
	v_cndmask_b32_e64 v6, 0, 32, s[36:37]
	v_ldexp_f32 v5, v5, v6
	v_log_f32_e32 v5, v5
	s_nop 0
	v_mul_f32_e32 v6, 0x3f317217, v5
	v_fma_f32 v6, v5, s27, -v6
	v_fmac_f32_e32 v6, 0x3377d1cf, v5
	v_fmac_f32_e32 v6, 0x3f317217, v5
	v_cmp_lt_f32_e64 s[38:39], |v5|, s40
	s_mov_b32 s27, 0x7f800000
	s_nop 0
	v_cndmask_b32_e64 v5, v5, v6, s[38:39]
	v_cndmask_b32_e64 v6, 0, v203, s[36:37]
	v_sub_f32_e32 v5, v5, v6
	v_cndmask_b32_e64 v3, v5, -v3, s[0:1]
	v_pk_mul_f32 v[16:17], v[2:3], s[50:51] op_sel_hi:[1,0]
	s_mov_b64 s[0:1], 0
	global_store_dwordx4 v[134:135], v[14:17], off
	s_and_saveexec_b64 s[36:37], s[30:31]
	s_xor_b64 s[36:37], exec, s[36:37]
	s_cbranch_execz .LBB0_452
	s_and_saveexec_b64 s[38:39], s[6:7]
	s_xor_b64 s[38:39], exec, s[38:39]
	s_cbranch_execz .LBB0_442
	v_lshlrev_b32_e32 v130, 2, v46
	v_lshl_add_u64 v[2:3], v[132:133], 0, v[130:131]
	v_add_co_u32_e32 v2, vcc, 0x2000, v2
	s_mov_b64 s[0:1], exec
	s_nop 0
	v_addc_co_u32_e32 v3, vcc, 0, v3, vcc
	global_load_dword v4, v[108:109], off offset:-32
	s_nop 0
	global_load_dword v2, v[2:3], off offset:2176
	s_nop 0
	global_load_dword v3, v[106:107], off offset:-32
	s_waitcnt vmcnt(1)
	v_add_f32_e32 v2, v2, v4
	v_mul_f32_e32 v4, 0x3fb8aa3b, v2
	v_exp_f32_e32 v4, v4
	s_waitcnt vmcnt(0)
	v_mul_f32_e32 v3, 0x3fb8aa3b, v3
	v_exp_f32_e32 v3, v3
	v_add_f32_e32 v4, 1.0, v4
	v_cmp_gt_f32_e32 vcc, s14, v4
	s_nop 1
	v_cndmask_b32_e64 v5, 0, 32, vcc
	v_ldexp_f32 v4, v4, v5
	v_log_f32_e32 v4, v4
	v_cndmask_b32_e32 v5, 0, v203, vcc
	v_mul_f32_e32 v6, 0x3f317217, v4
	v_fma_f32 v6, v4, s48, -v6
	v_fmac_f32_e32 v6, 0x3377d1cf, v4
	v_fmac_f32_e32 v6, 0x3f317217, v4
	v_cmp_lt_f32_e64 vcc, |v4|, s27
	s_mov_b32 s27, 0x41a00000
	s_nop 0
	v_cndmask_b32_e32 v4, v4, v6, vcc
	v_sub_f32_e32 v4, v4, v5
	v_cmp_lt_f32_e32 vcc, s27, v2
	s_nop 1
	v_cndmask_b32_e32 v2, v4, v2, vcc
	v_mul_f32_e64 v6, v2, -v3
	v_lshl_add_u32 v2, v128, 3, v47
